# L1 invalidate kept only at every second barrier of the layer loop (post-G1, post-G2, post-G3): any line is read, rewritten by another CU and re-read in three different phases, so every pair of consecu
# speedup vs baseline: 1.1792x; 1.0045x over previous
.Lbattn_scored:
	v_max3_f32 v7, v3, s61, v4
	v_max3_f32 v7, v7, v5, v8
	v_max3_f32 v7, v7, v9, v10
	v_max3_f32 v7, v7, v11, v13
	v_max3_f32 v7, v7, v14, v15
	v_max3_f32 v7, v7, v96, v97
	v_max3_f32 v7, v7, v98, v99
	v_max3_f32 v7, v7, v100, v101
	v_max3_f32 v7, v7, v80, v102
	v_max3_f32 v7, v7, v103, v104
	v_max3_f32 v7, v7, v105, v106
	v_max3_f32 v7, v7, v107, v108
	v_max3_f32 v7, v7, v88, v109
	v_max3_f32 v7, v7, v110, v111
	v_max3_f32 v7, v7, v177, v178
	v_max3_f32 v7, v7, v179, v2
	v_mov_b32_e32 v81, v7
	s_nop 1
	v_permlane32_swap_b32 v81, v7
	v_max3_f32 v7, v12, v7, v81
	v_cmp_eq_f32_e32 vcc, s61, v7
	v_sub_f32_e32 v180, v12, v7
	s_nop 0
	v_cndmask_b32_e64 v181, v7, 0, vcc
	v_exp_f32_e32 v180, v180
	v_sub_f32_e32 v3, v3, v181
	v_cndmask_b32_e64 v180, v180, 1.0, vcc
	v_pk_mul_f32 v[62:63], v[62:63], v[180:181] op_sel_hi:[1,0]
	v_pk_mul_f32 v[60:61], v[60:61], v[180:181] op_sel_hi:[1,0]
	v_pk_mul_f32 v[58:59], v[58:59], v[180:181] op_sel_hi:[1,0]
	v_pk_mul_f32 v[56:57], v[56:57], v[180:181] op_sel_hi:[1,0]
	v_pk_mul_f32 v[54:55], v[54:55], v[180:181] op_sel_hi:[1,0]
	v_pk_mul_f32 v[52:53], v[52:53], v[180:181] op_sel_hi:[1,0]
	v_pk_mul_f32 v[50:51], v[50:51], v[180:181] op_sel_hi:[1,0]
	v_pk_mul_f32 v[48:49], v[48:49], v[180:181] op_sel_hi:[1,0]
	v_pk_mul_f32 v[78:79], v[78:79], v[180:181] op_sel_hi:[1,0]
	v_pk_mul_f32 v[76:77], v[76:77], v[180:181] op_sel_hi:[1,0]
	v_pk_mul_f32 v[74:75], v[74:75], v[180:181] op_sel_hi:[1,0]
	v_pk_mul_f32 v[72:73], v[72:73], v[180:181] op_sel_hi:[1,0]
	v_pk_mul_f32 v[70:71], v[70:71], v[180:181] op_sel_hi:[1,0]
	v_pk_mul_f32 v[68:69], v[68:69], v[180:181] op_sel_hi:[1,0]
	v_pk_mul_f32 v[66:67], v[66:67], v[180:181] op_sel_hi:[1,0]
	v_pk_mul_f32 v[64:65], v[64:65], v[180:181] op_sel_hi:[1,0]
	v_exp_f32_e32 v3, v3
	v_sub_f32_e32 v4, v4, v181
	v_exp_f32_e32 v4, v4
	v_sub_f32_e32 v5, v5, v181
	v_exp_f32_e32 v5, v5
	v_sub_f32_e32 v8, v8, v181
	v_exp_f32_e32 v182, v8
	v_sub_f32_e32 v9, v9, v181
	v_add_f32_e32 v12, 0, v3
	v_exp_f32_e32 v183, v9
	v_sub_f32_e32 v9, v10, v181
	v_add_f32_e32 v12, v4, v12
	v_exp_f32_e32 v184, v9
	v_sub_f32_e32 v9, v11, v181
	v_add_f32_e32 v12, v5, v12
	v_exp_f32_e32 v185, v9
	v_sub_f32_e32 v9, v13, v181
	v_add_f32_e32 v8, v182, v12
	v_exp_f32_e32 v186, v9
	v_sub_f32_e32 v9, v14, v181
	v_add_f32_e32 v8, v183, v8
	v_cvt_pk_bf16_f32 v236, v3, v4
	v_cvt_pk_bf16_f32 v237, v5, v182
	v_cvt_pk_bf16_f32 v238, v183, v184
	v_cvt_pk_bf16_f32 v239, v185, v186
	s_waitcnt lgkmcnt(0)
	s_nop 0
	v_mfma_f32_32x32x16_bf16 v[48:63], v[16:19], v[236:239], v[48:63]
	v_mfma_f32_32x32x16_bf16 v[64:79], v[20:23], v[236:239], v[64:79]
	v_exp_f32_e32 v9, v9
	v_sub_f32_e32 v10, v15, v181
	v_add_f32_e32 v8, v184, v8
	v_exp_f32_e32 v10, v10
	v_sub_f32_e32 v11, v96, v181
	v_add_f32_e32 v8, v185, v8
	v_exp_f32_e32 v11, v11
	v_sub_f32_e32 v12, v97, v181
	v_add_f32_e32 v8, v186, v8
	v_exp_f32_e32 v12, v12
	v_sub_f32_e32 v13, v98, v181
	v_add_f32_e32 v8, v9, v8
	v_exp_f32_e32 v13, v13
	v_sub_f32_e32 v14, v99, v181
	v_add_f32_e32 v8, v10, v8
	v_exp_f32_e32 v14, v14
	v_sub_f32_e32 v15, v100, v181
	v_add_f32_e32 v8, v11, v8
	v_exp_f32_e32 v15, v15
	v_sub_f32_e32 v81, v101, v181
	v_add_f32_e32 v8, v12, v8
	v_exp_f32_e32 v81, v81
	v_sub_f32_e32 v80, v80, v181
	v_add_f32_e32 v8, v13, v8
	v_cvt_pk_bf16_f32 v236, v9, v10
	v_cvt_pk_bf16_f32 v237, v11, v12
	v_cvt_pk_bf16_f32 v238, v13, v14
	v_cvt_pk_bf16_f32 v239, v15, v81
	s_nop 0
	s_nop 0
	v_mfma_f32_32x32x16_bf16 v[48:63], v[24:27], v[236:239], v[48:63]
	v_mfma_f32_32x32x16_bf16 v[64:79], v[28:31], v[236:239], v[64:79]
	v_exp_f32_e32 v80, v80
	v_sub_f32_e32 v82, v102, v181
	v_add_f32_e32 v8, v14, v8
	v_exp_f32_e32 v82, v82
	v_sub_f32_e32 v83, v103, v181
	v_add_f32_e32 v8, v15, v8
	v_exp_f32_e32 v83, v83
	v_sub_f32_e32 v84, v104, v181
	v_add_f32_e32 v8, v81, v8
	v_exp_f32_e32 v84, v84
	v_sub_f32_e32 v85, v105, v181
	v_add_f32_e32 v8, v80, v8
	v_exp_f32_e32 v85, v85
	v_sub_f32_e32 v86, v106, v181
	v_add_f32_e32 v8, v82, v8
	v_exp_f32_e32 v86, v86
	v_sub_f32_e32 v87, v107, v181
	v_add_f32_e32 v8, v83, v8
	v_exp_f32_e32 v87, v87
	v_sub_f32_e32 v89, v108, v181
	v_add_f32_e32 v8, v84, v8
	v_exp_f32_e32 v89, v89
	v_sub_f32_e32 v88, v88, v181
	v_add_f32_e32 v8, v85, v8
	v_cvt_pk_bf16_f32 v236, v80, v82
	v_cvt_pk_bf16_f32 v237, v83, v84
	v_cvt_pk_bf16_f32 v238, v85, v86
	v_cvt_pk_bf16_f32 v239, v87, v89
	s_nop 0
	s_nop 0
	v_mfma_f32_32x32x16_bf16 v[48:63], v[32:35], v[236:239], v[48:63]
	v_mfma_f32_32x32x16_bf16 v[64:79], v[36:39], v[236:239], v[64:79]
	v_exp_f32_e32 v88, v88
	v_sub_f32_e32 v90, v109, v181
	v_add_f32_e32 v8, v86, v8
	v_exp_f32_e32 v90, v90
	v_sub_f32_e32 v91, v110, v181
	v_add_f32_e32 v8, v87, v8
	v_exp_f32_e32 v91, v91
	v_sub_f32_e32 v92, v111, v181
	v_add_f32_e32 v8, v89, v8
	v_exp_f32_e32 v92, v92
	v_sub_f32_e32 v93, v177, v181
	v_add_f32_e32 v8, v88, v8
	v_exp_f32_e32 v93, v93
	v_sub_f32_e32 v94, v178, v181
	v_add_f32_e32 v8, v90, v8
	v_exp_f32_e32 v94, v94
	v_sub_f32_e32 v95, v179, v181
	v_add_f32_e32 v8, v91, v8
	v_exp_f32_e32 v95, v95
	v_sub_f32_e32 v2, v2, v181
	v_add_f32_e32 v8, v92, v8
	v_exp_f32_e32 v96, v2
	v_add_f32_e32 v8, v93, v8
	v_add_f32_e32 v8, v94, v8
	v_add_f32_e32 v8, v95, v8
	v_add_f32_e32 v8, v96, v8
	v_cvt_pk_bf16_f32 v236, v88, v90
	v_cvt_pk_bf16_f32 v237, v91, v92
	v_cvt_pk_bf16_f32 v238, v93, v94
	v_cvt_pk_bf16_f32 v239, v95, v96
	v_fmac_f32_e32 v8, v176, v180
	s_and_b64 vcc, exec, s[6:7]
	s_mov_b64 s[6:7], 0
	s_mov_b32 s20, 1
	v_mfma_f32_32x32x16_bf16 v[48:63], v[40:43], v[236:239], v[48:63]
	v_mfma_f32_32x32x16_bf16 v[64:79], v[44:47], v[236:239], v[64:79]
	s_cbranch_vccnz .LBB0_548
	s_mov_b64 s[0:1], 0

.LBB0_552:
	v_cndmask_b32_e64 v2, 0, 1, s[0:1]
	s_mul_i32 s0, s4, 0x2400
	v_add_u32_e32 v11, s0, v175
	v_cmp_ne_u32_e32 vcc, 1, v2
	ds_read_b128 v[2:5], v11
	ds_read_b128 v[12:15], v11 offset:4608
	ds_read_b128 v[6:9], v11 offset:32
	ds_read_b128 v[124:127], v11 offset:4640
	v_lshl_add_u32 v110, s4, 7, v174
	v_add_u32_e32 v111, 0x4800, v110
	v_add_u32_e32 v110, 0x6800, v110
	ds_read2_b64 v[82:85], v111 offset1:2
	ds_read2_b64 v[86:89], v110 offset0:64 offset1:66
	ds_read2_b64 v[90:93], v111 offset0:4 offset1:6
	ds_read2_b64 v[94:97], v110 offset0:68 offset1:70
	ds_read2_b64 v[98:101], v111 offset0:8 offset1:10
	ds_read2_b64 v[102:105], v110 offset0:72 offset1:74
	ds_read2_b64 v[106:109], v111 offset0:12 offset1:14
	ds_read2_b64 v[120:123], v110 offset0:76 offset1:78
	v_mov_b32_e32 v10, v164
	v_mov_b32_e32 v80, v165
	s_and_b64 vcc, exec, vcc
	s_waitcnt lgkmcnt(11)
	v_mfma_f32_32x32x16_bf16 v[64:79], v[2:5], v[112:115], 0
	s_waitcnt lgkmcnt(10)
	v_mfma_f32_32x32x16_bf16 v[48:63], v[12:15], v[112:115], 0
	s_waitcnt lgkmcnt(9)
	v_mfma_f32_32x32x16_bf16 v[64:79], v[6:9], v[116:119], v[64:79]
	s_waitcnt lgkmcnt(8)
	v_mfma_f32_32x32x16_bf16 v[48:63], v[124:127], v[116:119], v[48:63]
	s_nop 9
	v_max3_f32 v2, v64, s61, v65
	v_max3_f32 v2, v2, v66, v67
	v_max3_f32 v2, v2, v68, v69
	v_max3_f32 v2, v2, v70, v71
	v_max3_f32 v2, v2, v72, v73
	v_max3_f32 v2, v2, v74, v75
	v_max3_f32 v2, v2, v76, v77
	v_max3_f32 v2, v2, v78, v79
	v_max3_f32 v2, v2, v48, v49
	v_max3_f32 v2, v2, v50, v51
	v_max3_f32 v2, v2, v52, v53
	v_max3_f32 v2, v2, v54, v55
	v_max3_f32 v2, v2, v56, v57
	v_max3_f32 v2, v2, v58, v59
	v_max3_f32 v2, v2, v60, v61
	v_max3_f32 v2, v2, v62, v63
	v_mul_f32_e32 v2, s9, v2
	v_mov_b32_e32 v3, v2
	s_nop 1
	v_permlane32_swap_b32 v3, v2
	v_max3_f32 v164, v10, v2, v3
	v_cmp_eq_f32_e64 s[0:1], s61, v164
	v_sub_f32_e32 v2, v10, v164
	v_exp_f32_e32 v2, v2
	v_cndmask_b32_e64 v3, v164, 0, s[0:1]
	v_cndmask_b32_e64 v110, v2, 1.0, s[0:1]
	v_pk_mul_f32 v[46:47], v[46:47], v[110:111] op_sel_hi:[1,0]
	v_pk_mul_f32 v[44:45], v[44:45], v[110:111] op_sel_hi:[1,0]
	v_pk_mul_f32 v[42:43], v[42:43], v[110:111] op_sel_hi:[1,0]
	v_pk_mul_f32 v[40:41], v[40:41], v[110:111] op_sel_hi:[1,0]
	v_pk_mul_f32 v[38:39], v[38:39], v[110:111] op_sel_hi:[1,0]
	v_pk_mul_f32 v[36:37], v[36:37], v[110:111] op_sel_hi:[1,0]
	v_pk_mul_f32 v[34:35], v[34:35], v[110:111] op_sel_hi:[1,0]
	v_pk_mul_f32 v[32:33], v[32:33], v[110:111] op_sel_hi:[1,0]
	v_pk_mul_f32 v[30:31], v[30:31], v[110:111] op_sel_hi:[1,0]
	v_pk_mul_f32 v[28:29], v[28:29], v[110:111] op_sel_hi:[1,0]
	v_pk_mul_f32 v[26:27], v[26:27], v[110:111] op_sel_hi:[1,0]
	v_pk_mul_f32 v[24:25], v[24:25], v[110:111] op_sel_hi:[1,0]
	v_pk_mul_f32 v[22:23], v[22:23], v[110:111] op_sel_hi:[1,0]
	v_pk_mul_f32 v[20:21], v[20:21], v[110:111] op_sel_hi:[1,0]
	v_pk_mul_f32 v[18:19], v[18:19], v[110:111] op_sel_hi:[1,0]
	v_pk_mul_f32 v[16:17], v[16:17], v[110:111] op_sel_hi:[1,0]
	s_mov_b64 s[0:1], 0
	s_mov_b32 s4, 1
	v_fma_f32 v4, s9, v64, -v3
	v_exp_f32_e32 v4, v4
	v_fma_f32 v6, s9, v65, -v3
	v_exp_f32_e32 v64, v6
	v_fma_f32 v6, s9, v66, -v3
	v_exp_f32_e32 v65, v6
	v_fma_f32 v6, s9, v67, -v3
	v_exp_f32_e32 v66, v6
	v_fma_f32 v6, s9, v68, -v3
	v_add_f32_e32 v5, 0, v4
	v_exp_f32_e32 v67, v6
	v_fma_f32 v6, s9, v69, -v3
	v_add_f32_e32 v5, v64, v5
	v_exp_f32_e32 v68, v6
	v_fma_f32 v6, s9, v70, -v3
	v_add_f32_e32 v5, v65, v5
	v_exp_f32_e32 v69, v6
	v_fma_f32 v6, s9, v71, -v3
	v_add_f32_e32 v5, v66, v5
	v_exp_f32_e32 v70, v6
	v_fma_f32 v6, s9, v72, -v3
	v_add_f32_e32 v5, v67, v5
	v_cvt_pk_bf16_f32 v124, v4, v64
	v_cvt_pk_bf16_f32 v125, v65, v66
	v_cvt_pk_bf16_f32 v126, v67, v68
	v_cvt_pk_bf16_f32 v127, v69, v70
	s_waitcnt lgkmcnt(0)
	s_nop 1
	v_mfma_f32_32x32x16_bf16 v[32:47], v[82:85], v[124:127], v[32:47]
	v_mfma_f32_32x32x16_bf16 v[16:31], v[86:89], v[124:127], v[16:31]
	v_exp_f32_e32 v6, v6
	v_fma_f32 v7, s9, v73, -v3
	v_add_f32_e32 v5, v68, v5
	v_exp_f32_e32 v7, v7
	v_fma_f32 v8, s9, v74, -v3
	v_add_f32_e32 v5, v69, v5
	v_exp_f32_e32 v8, v8
	v_fma_f32 v9, s9, v75, -v3
	v_add_f32_e32 v5, v70, v5
	v_exp_f32_e32 v9, v9
	v_fma_f32 v10, s9, v76, -v3
	v_add_f32_e32 v5, v6, v5
	v_exp_f32_e32 v10, v10
	v_fma_f32 v11, s9, v77, -v3
	v_add_f32_e32 v5, v7, v5
	v_exp_f32_e32 v11, v11
	v_fma_f32 v12, s9, v78, -v3
	v_add_f32_e32 v5, v8, v5
	v_exp_f32_e32 v12, v12
	v_fma_f32 v13, s9, v79, -v3
	v_add_f32_e32 v5, v9, v5
	v_exp_f32_e32 v14, v13
	v_fma_f32 v13, s9, v48, -v3
	v_add_f32_e32 v5, v10, v5
	v_cvt_pk_bf16_f32 v124, v6, v7
	v_cvt_pk_bf16_f32 v125, v8, v9
	v_cvt_pk_bf16_f32 v126, v10, v11
	v_cvt_pk_bf16_f32 v127, v12, v14
	s_nop 1
	v_mfma_f32_32x32x16_bf16 v[32:47], v[90:93], v[124:127], v[32:47]
	v_mfma_f32_32x32x16_bf16 v[16:31], v[94:97], v[124:127], v[16:31]
	v_exp_f32_e32 v13, v13
	v_fma_f32 v15, s9, v49, -v3
	v_add_f32_e32 v5, v11, v5
	v_exp_f32_e32 v15, v15
	v_fma_f32 v48, s9, v50, -v3
	v_add_f32_e32 v5, v12, v5
	v_exp_f32_e32 v48, v48
	v_fma_f32 v49, s9, v51, -v3
	v_add_f32_e32 v5, v14, v5
	v_exp_f32_e32 v49, v49
	v_fma_f32 v50, s9, v52, -v3
	v_add_f32_e32 v5, v13, v5
	v_exp_f32_e32 v50, v50
	v_fma_f32 v51, s9, v53, -v3
	v_add_f32_e32 v5, v15, v5
	v_exp_f32_e32 v51, v51
	v_fma_f32 v52, s9, v54, -v3
	v_add_f32_e32 v5, v48, v5
	v_exp_f32_e32 v52, v52
	v_fma_f32 v53, s9, v55, -v3
	v_add_f32_e32 v5, v49, v5
	v_exp_f32_e32 v54, v53
	v_fma_f32 v53, s9, v56, -v3
	v_add_f32_e32 v5, v50, v5
	v_cvt_pk_bf16_f32 v124, v13, v15
	v_cvt_pk_bf16_f32 v125, v48, v49
	v_cvt_pk_bf16_f32 v126, v50, v51
	v_cvt_pk_bf16_f32 v127, v52, v54
	s_nop 1
	v_mfma_f32_32x32x16_bf16 v[32:47], v[98:101], v[124:127], v[32:47]
	v_mfma_f32_32x32x16_bf16 v[16:31], v[102:105], v[124:127], v[16:31]
	v_exp_f32_e32 v53, v53
	v_fma_f32 v55, s9, v57, -v3
	v_add_f32_e32 v5, v51, v5
	v_exp_f32_e32 v55, v55
	v_fma_f32 v56, s9, v58, -v3
	v_add_f32_e32 v5, v52, v5
	v_exp_f32_e32 v56, v56
	v_fma_f32 v57, s9, v59, -v3
	v_add_f32_e32 v5, v54, v5
	v_exp_f32_e32 v57, v57
	v_fma_f32 v58, s9, v60, -v3
	v_add_f32_e32 v5, v53, v5
	v_exp_f32_e32 v58, v58
	v_fma_f32 v59, s9, v61, -v3
	v_add_f32_e32 v5, v55, v5
	v_exp_f32_e32 v59, v59
	v_fma_f32 v60, s9, v62, -v3
	v_add_f32_e32 v5, v56, v5
	v_exp_f32_e32 v60, v60
	v_fma_f32 v3, s9, v63, -v3
	v_add_f32_e32 v5, v57, v5
	v_exp_f32_e32 v61, v3
	v_add_f32_e32 v5, v58, v5
	v_add_f32_e32 v5, v59, v5
	v_add_f32_e32 v5, v60, v5
	v_add_f32_e32 v165, v61, v5
	v_cvt_pk_bf16_f32 v124, v53, v55
	v_cvt_pk_bf16_f32 v125, v56, v57
	v_cvt_pk_bf16_f32 v126, v58, v59
	v_cvt_pk_bf16_f32 v127, v60, v61
	v_fmac_f32_e32 v165, v80, v110
	s_nop 0
	v_mfma_f32_32x32x16_bf16 v[32:47], v[106:109], v[124:127], v[32:47]
	v_mfma_f32_32x32x16_bf16 v[16:31], v[120:123], v[124:127], v[16:31]
	s_cbranch_vccz .LBB0_552
	s_nop 9
	v_mov_b64_e32 v[62:63], v[46:47]
	s_nop 1
	v_mov_b64_e32 v[78:79], v[30:31]
	v_mov_b64_e32 v[60:61], v[44:45]
	v_mov_b64_e32 v[58:59], v[42:43]
	v_mov_b64_e32 v[56:57], v[40:41]
	v_mov_b64_e32 v[54:55], v[38:39]
	v_mov_b64_e32 v[52:53], v[36:37]
	v_mov_b64_e32 v[50:51], v[34:35]
	v_mov_b64_e32 v[48:49], v[32:33]
	v_mov_b64_e32 v[76:77], v[28:29]
	v_mov_b64_e32 v[74:75], v[26:27]
	v_mov_b64_e32 v[72:73], v[24:25]
	v_mov_b64_e32 v[70:71], v[22:23]
	v_mov_b64_e32 v[68:69], v[20:21]
	v_mov_b64_e32 v[66:67], v[18:19]
	v_mov_b64_e32 v[64:65], v[16:17]
	v_mov_b32_e32 v7, v164
	v_mov_b32_e32 v8, v165
